# S5 B-row cache touches halved: one 16-byte touch per lane and tile row (same cache line as the second) (v60 + pfhalf)
# speedup vs baseline: 1.0029x; 1.0011x over previous
.LBB0_788:
	s_andn2_saveexec_b64 s[14:15], s[14:15]
	v_mul_f32_e64 v4, |v9|, s94
	v_rndne_f32_e32 v4, v4
	v_cvt_i32_f32_e32 v13, v4
	v_fma_f32 v12, v4, s95, |v9|
	v_fmac_f32_e32 v12, 0xb3a22168, v4
	v_fmac_f32_e32 v12, 0xa7c234c4, v4
	s_or_b64 exec, exec, s[14:15]
	s_or_b32 s2, s52, s9
	s_ashr_i32 s3, s2, 31
	v_mov_b32_e32 v4, 0
	s_lshl_b64 s[96:97], s[2:3], 10
	v_mov_b32_e32 v5, v4
	v_mov_b32_e32 v6, v4
	v_mov_b32_e32 v7, v4
	s_and_saveexec_b64 s[14:15], s[40:41]
	s_cbranch_execz .LBB0_792
	s_waitcnt vmcnt(0)
	v_max_f32_e32 v4, v11, v11
	v_min_f32_e32 v4, 0xb8d1b717, v4
	v_mul_f32_e32 v5, v105, v4
	v_mul_f32_e32 v6, 0x3fb8aa3b, v5
	v_fma_f32 v7, v5, s27, -v6
	v_rndne_f32_e32 v11, v6
	v_fmac_f32_e32 v7, 0x32a5705f, v5
	v_sub_f32_e32 v6, v6, v11
	v_add_f32_e32 v6, v6, v7
	v_exp_f32_e32 v6, v6
	v_cvt_i32_f32_e32 v7, v11
	v_cmp_ngt_f32_e32 vcc, s29, v5
	v_ldexp_f32 v6, v6, v7
	v_and_b32_e32 v7, 1, v13
	v_cndmask_b32_e32 v6, 0, v6, vcc
	v_cmp_nlt_f32_e32 vcc, s10, v5
	v_cmp_eq_u32_e64 s[46:47], 0, v7
	v_mul_f32_e32 v7, v12, v12
	v_cndmask_b32_e32 v5, v223, v6, vcc
	v_cmp_class_f32_e64 vcc, v9, s28
	v_xor_b32_e32 v6, v10, v9
	v_fmamk_f32 v9, v7, 0xb94c1982, v219
	v_fmaak_f32 v9, v7, v9, 0xbe2aaa9d
	v_mul_f32_e32 v9, v7, v9
	v_fmac_f32_e32 v12, v12, v9
	v_fmamk_f32 v9, v7, 0x37d75334, v220
	v_fmaak_f32 v9, v7, v9, 0x3d2aabf7
	v_fmaak_f32 v9, v7, v9, 0xbf000004
	v_fma_f32 v7, v7, v9, 1.0
	v_cndmask_b32_e64 v9, v7, v12, s[46:47]
	v_lshlrev_b32_e32 v10, 30, v13
	v_xor_b32_e32 v6, v6, v9
	v_xor_b32_e32 v9, 0x80000000, v12
	v_and_b32_e32 v11, 0x80000000, v10
	v_cndmask_b32_e64 v7, v9, v7, s[46:47]
	v_xor_b32_e32 v6, v6, v11
	v_bitop3_b32 v7, v7, v10, s33 bitop3:0x78
	v_cndmask_b32_e32 v6, v251, v6, vcc
	v_cndmask_b32_e32 v7, v251, v7, vcc
	v_mul_f32_e32 v6, v5, v6
	v_fma_f32 v10, v5, v7, -1.0
	v_mov_b32_e32 v7, v4
	v_mov_b32_e32 v11, v8
	v_pk_mul_f32 v[12:13], v[4:5], v[6:7] op_sel_hi:[0,1]
	v_pk_mul_f32 v[14:15], v[8:9], v[10:11] op_sel_hi:[0,1]
	v_sub_f32_e32 v5, v12, v14
	v_add_f32_e32 v7, v13, v15
	v_div_scale_f32 v9, s[2:3], v7, v7, v5
	v_rcp_f32_e32 v11, v9
	s_nop 0
	v_fma_f32 v12, -v9, v11, 1.0
	v_fmac_f32_e32 v11, v12, v11
	v_div_scale_f32 v12, vcc, v5, v7, v5
	v_mul_f32_e32 v13, v12, v11
	v_fma_f32 v14, -v9, v13, v12
	v_fmac_f32_e32 v13, v14, v11
	v_fma_f32 v9, -v9, v13, v12
	v_div_fmas_f32 v9, v9, v11, v13
	v_div_fixup_f32 v20, v9, v7, v5
	v_mov_b32_e32 v5, v8
	v_mov_b32_e32 v11, v6
	v_pk_mul_f32 v[4:5], v[4:5], v[10:11]
	s_nop 0
	v_add_f32_e32 v4, v4, v5
	v_div_scale_f32 v5, s[2:3], v7, v7, v4
	v_rcp_f32_e32 v6, v5
	s_nop 0
	v_fma_f32 v8, -v5, v6, 1.0
	v_fmac_f32_e32 v6, v8, v6
	v_div_scale_f32 v8, vcc, v4, v7, v4
	v_mul_f32_e32 v9, v8, v6
	v_fma_f32 v10, -v5, v9, v8
	v_fmac_f32_e32 v9, v10, v6
	v_fma_f32 v5, -v5, v9, v8
	v_div_fmas_f32 v5, v5, v6, v9
	v_div_fixup_f32 v22, v5, v7, v4
	v_mov_b32_e32 v5, s97
	v_or_b32_e32 v4, s96, v92
	v_lshlrev_b64 v[4:5], 2, v[4:5]
	v_lshl_add_u64 v[8:9], v[112:113], 0, v[4:5]
	v_lshl_add_u64 v[16:17], v[114:115], 0, v[4:5]
	global_load_dwordx4 v[208:211], v[8:9], off offset:512
	global_load_dwordx4 v[208:211], v[16:17], off offset:512
	global_load_dwordx4 v[208:211], v[8:9], off offset:1024
	global_load_dwordx4 v[208:211], v[16:17], off offset:1024
	global_load_dwordx4 v[208:211], v[8:9], off offset:1536
	global_load_dwordx4 v[208:211], v[16:17], off offset:1536
	global_load_dwordx4 v[208:211], v[8:9], off offset:2048
	global_load_dwordx4 v[208:211], v[16:17], off offset:2048
	global_load_dwordx4 v[208:211], v[8:9], off offset:2560
	global_load_dwordx4 v[208:211], v[16:17], off offset:2560
	global_load_dwordx4 v[208:211], v[8:9], off offset:3072
	global_load_dwordx4 v[208:211], v[16:17], off offset:3072
	global_load_dwordx4 v[208:211], v[8:9], off offset:3584
	global_load_dwordx4 v[208:211], v[16:17], off offset:3584
	global_load_dwordx4 v[4:7], v[8:9], off offset:16
	global_load_dwordx4 v[12:15], v[8:9], off
	s_nop 0
	global_load_dwordx4 v[8:11], v[16:17], off offset:16
	s_nop 0
	global_load_dwordx4 v[16:19], v[16:17], off
	s_waitcnt vmcnt(0)
	v_pk_mul_f32 v[24:25], v[22:23], v[18:19] op_sel_hi:[0,1]
	v_pk_mul_f32 v[26:27], v[22:23], v[16:17] op_sel_hi:[0,1]
	v_pk_mul_f32 v[18:19], v[20:21], v[18:19] op_sel_hi:[0,1]
	v_pk_mul_f32 v[16:17], v[20:21], v[16:17] op_sel_hi:[0,1]
	v_pk_fma_f32 v[26:27], v[20:21], v[12:13], v[26:27] op_sel_hi:[0,1,1]
	v_pk_fma_f32 v[24:25], v[20:21], v[14:15], v[24:25] op_sel_hi:[0,1,1]
	v_pk_fma_f32 v[12:13], v[22:23], v[12:13], v[16:17] op_sel_hi:[0,1,1] neg_lo:[0,0,1] neg_hi:[0,0,1]
	v_pk_fma_f32 v[14:15], v[22:23], v[14:15], v[18:19] op_sel_hi:[0,1,1] neg_lo:[0,0,1] neg_hi:[0,0,1]
	v_cndmask_b32_e64 v16, v25, v15, s[44:45]
	v_cndmask_b32_e64 v17, v24, v14, s[44:45]
	v_cndmask_b32_e64 v18, v27, v13, s[44:45]
	v_cndmask_b32_e64 v19, v26, v12, s[44:45]
	v_pk_mul_f32 v[12:13], v[22:23], v[10:11] op_sel_hi:[0,1]
	v_pk_mul_f32 v[14:15], v[22:23], v[8:9] op_sel_hi:[0,1]
	v_pk_mul_f32 v[10:11], v[20:21], v[10:11] op_sel_hi:[0,1]
	v_pk_mul_f32 v[8:9], v[20:21], v[8:9] op_sel_hi:[0,1]
	v_pk_fma_f32 v[14:15], v[20:21], v[4:5], v[14:15] op_sel_hi:[0,1,1]
	v_pk_fma_f32 v[12:13], v[20:21], v[6:7], v[12:13] op_sel_hi:[0,1,1]
	v_pk_fma_f32 v[4:5], v[22:23], v[4:5], v[8:9] op_sel_hi:[0,1,1] neg_lo:[0,0,1] neg_hi:[0,0,1]
	v_pk_fma_f32 v[6:7], v[22:23], v[6:7], v[10:11] op_sel_hi:[0,1,1] neg_lo:[0,0,1] neg_hi:[0,0,1]
	v_cndmask_b32_e64 v7, v13, v7, s[44:45]
	v_cndmask_b32_e64 v8, v12, v6, s[44:45]
	v_cndmask_b32_e64 v6, v15, v5, s[44:45]
	v_cndmask_b32_e64 v9, v14, v4, s[44:45]
	v_cvt_pk_bf16_f32 v4, v19, v18
	v_cvt_pk_bf16_f32 v5, v17, v16
	v_cvt_pk_bf16_f32 v6, v9, v6
	v_cvt_pk_bf16_f32 v7, v8, v7

.LBB0_857:
	s_andn2_saveexec_b64 s[14:15], s[14:15]
	v_mul_f32_e64 v4, |v9|, s94
	v_rndne_f32_e32 v4, v4
	v_cvt_i32_f32_e32 v13, v4
	v_fma_f32 v12, v4, s95, |v9|
	v_fmac_f32_e32 v12, 0xb3a22168, v4
	v_fmac_f32_e32 v12, 0xa7c234c4, v4
	s_or_b64 exec, exec, s[14:15]
	s_or_b32 s2, s7, s9
	s_ashr_i32 s3, s2, 31
	v_mov_b32_e32 v4, 0
	s_lshl_b64 s[58:59], s[2:3], 10
	v_mov_b32_e32 v5, v4
	v_mov_b32_e32 v6, v4
	v_mov_b32_e32 v7, v4
	s_and_saveexec_b64 s[14:15], s[40:41]
	s_cbranch_execz .LBB0_861
	s_waitcnt vmcnt(0)
	v_max_f32_e32 v4, v11, v11
	v_min_f32_e32 v4, 0xb8d1b717, v4
	v_mul_f32_e32 v5, v103, v4
	v_mul_f32_e32 v6, 0x3fb8aa3b, v5
	v_fma_f32 v7, v5, s27, -v6
	v_rndne_f32_e32 v11, v6
	v_fmac_f32_e32 v7, 0x32a5705f, v5
	v_sub_f32_e32 v6, v6, v11
	v_add_f32_e32 v6, v6, v7
	v_exp_f32_e32 v6, v6
	v_cvt_i32_f32_e32 v7, v11
	v_cmp_ngt_f32_e32 vcc, s29, v5
	v_ldexp_f32 v6, v6, v7
	v_and_b32_e32 v7, 1, v13
	v_cndmask_b32_e32 v6, 0, v6, vcc
	v_cmp_nlt_f32_e32 vcc, s10, v5
	v_cmp_eq_u32_e64 s[46:47], 0, v7
	v_mul_f32_e32 v7, v12, v12
	v_cndmask_b32_e32 v5, v223, v6, vcc
	v_cmp_class_f32_e64 vcc, v9, s28
	v_xor_b32_e32 v6, v10, v9
	v_fmamk_f32 v9, v7, 0xb94c1982, v219
	v_fmaak_f32 v9, v7, v9, 0xbe2aaa9d
	v_mul_f32_e32 v9, v7, v9
	v_fmac_f32_e32 v12, v12, v9
	v_fmamk_f32 v9, v7, 0x37d75334, v220
	v_fmaak_f32 v9, v7, v9, 0x3d2aabf7
	v_fmaak_f32 v9, v7, v9, 0xbf000004
	v_fma_f32 v7, v7, v9, 1.0
	v_cndmask_b32_e64 v9, v7, v12, s[46:47]
	v_lshlrev_b32_e32 v10, 30, v13
	v_xor_b32_e32 v6, v6, v9
	v_xor_b32_e32 v9, 0x80000000, v12
	v_and_b32_e32 v11, 0x80000000, v10
	v_cndmask_b32_e64 v7, v9, v7, s[46:47]
	v_xor_b32_e32 v6, v6, v11
	v_bitop3_b32 v7, v7, v10, s33 bitop3:0x78
	v_cndmask_b32_e32 v6, v251, v6, vcc
	v_cndmask_b32_e32 v7, v251, v7, vcc
	v_mul_f32_e32 v6, v5, v6
	v_fma_f32 v10, v5, v7, -1.0
	v_mov_b32_e32 v7, v4
	v_mov_b32_e32 v11, v8
	v_pk_mul_f32 v[12:13], v[4:5], v[6:7] op_sel_hi:[0,1]
	v_pk_mul_f32 v[14:15], v[8:9], v[10:11] op_sel_hi:[0,1]
	v_sub_f32_e32 v5, v12, v14
	v_add_f32_e32 v7, v13, v15
	v_div_scale_f32 v9, s[2:3], v7, v7, v5
	v_rcp_f32_e32 v11, v9
	s_nop 0
	v_fma_f32 v12, -v9, v11, 1.0
	v_fmac_f32_e32 v11, v12, v11
	v_div_scale_f32 v12, vcc, v5, v7, v5
	v_mul_f32_e32 v13, v12, v11
	v_fma_f32 v14, -v9, v13, v12
	v_fmac_f32_e32 v13, v14, v11
	v_fma_f32 v9, -v9, v13, v12
	v_div_fmas_f32 v9, v9, v11, v13
	v_div_fixup_f32 v20, v9, v7, v5
	v_mov_b32_e32 v5, v8
	v_mov_b32_e32 v11, v6
	v_pk_mul_f32 v[4:5], v[4:5], v[10:11]
	s_nop 0
	v_add_f32_e32 v4, v4, v5
	v_div_scale_f32 v5, s[2:3], v7, v7, v4
	v_rcp_f32_e32 v6, v5
	s_nop 0
	v_fma_f32 v8, -v5, v6, 1.0
	v_fmac_f32_e32 v6, v8, v6
	v_div_scale_f32 v8, vcc, v4, v7, v4
	v_mul_f32_e32 v9, v8, v6
	v_fma_f32 v10, -v5, v9, v8
	v_fmac_f32_e32 v9, v10, v6
	v_fma_f32 v5, -v5, v9, v8
	v_div_fmas_f32 v5, v5, v6, v9
	v_div_fixup_f32 v22, v5, v7, v4
	v_mov_b32_e32 v5, s59
	v_or_b32_e32 v4, s58, v92
	v_lshlrev_b64 v[4:5], 2, v[4:5]
	v_lshl_add_u64 v[8:9], v[112:113], 0, v[4:5]
	v_lshl_add_u64 v[16:17], v[114:115], 0, v[4:5]
	global_load_dwordx4 v[208:211], v[8:9], off offset:512
	global_load_dwordx4 v[208:211], v[16:17], off offset:512
	global_load_dwordx4 v[208:211], v[8:9], off offset:1024
	global_load_dwordx4 v[208:211], v[16:17], off offset:1024
	global_load_dwordx4 v[208:211], v[8:9], off offset:1536
	global_load_dwordx4 v[208:211], v[16:17], off offset:1536
	global_load_dwordx4 v[208:211], v[8:9], off offset:2048
	global_load_dwordx4 v[208:211], v[16:17], off offset:2048
	global_load_dwordx4 v[208:211], v[8:9], off offset:2560
	global_load_dwordx4 v[208:211], v[16:17], off offset:2560
	global_load_dwordx4 v[208:211], v[8:9], off offset:3072
	global_load_dwordx4 v[208:211], v[16:17], off offset:3072
	global_load_dwordx4 v[208:211], v[8:9], off offset:3584
	global_load_dwordx4 v[208:211], v[16:17], off offset:3584
	global_load_dwordx4 v[4:7], v[8:9], off offset:16
	global_load_dwordx4 v[12:15], v[8:9], off
	s_nop 0
	global_load_dwordx4 v[8:11], v[16:17], off offset:16
	s_nop 0
	global_load_dwordx4 v[16:19], v[16:17], off
	s_waitcnt vmcnt(0)
	v_pk_mul_f32 v[24:25], v[22:23], v[18:19] op_sel_hi:[0,1]
	v_pk_mul_f32 v[26:27], v[22:23], v[16:17] op_sel_hi:[0,1]
	v_pk_mul_f32 v[18:19], v[20:21], v[18:19] op_sel_hi:[0,1]
	v_pk_mul_f32 v[16:17], v[20:21], v[16:17] op_sel_hi:[0,1]
	v_pk_fma_f32 v[26:27], v[20:21], v[12:13], v[26:27] op_sel_hi:[0,1,1]
	v_pk_fma_f32 v[24:25], v[20:21], v[14:15], v[24:25] op_sel_hi:[0,1,1]
	v_pk_fma_f32 v[12:13], v[22:23], v[12:13], v[16:17] op_sel_hi:[0,1,1] neg_lo:[0,0,1] neg_hi:[0,0,1]
	v_pk_fma_f32 v[14:15], v[22:23], v[14:15], v[18:19] op_sel_hi:[0,1,1] neg_lo:[0,0,1] neg_hi:[0,0,1]
	v_cndmask_b32_e64 v16, v25, v15, s[44:45]
	v_cndmask_b32_e64 v17, v24, v14, s[44:45]
	v_cndmask_b32_e64 v18, v27, v13, s[44:45]
	v_cndmask_b32_e64 v19, v26, v12, s[44:45]
	v_pk_mul_f32 v[12:13], v[22:23], v[10:11] op_sel_hi:[0,1]
	v_pk_mul_f32 v[14:15], v[22:23], v[8:9] op_sel_hi:[0,1]
	v_pk_mul_f32 v[10:11], v[20:21], v[10:11] op_sel_hi:[0,1]
	v_pk_mul_f32 v[8:9], v[20:21], v[8:9] op_sel_hi:[0,1]
	v_pk_fma_f32 v[14:15], v[20:21], v[4:5], v[14:15] op_sel_hi:[0,1,1]
	v_pk_fma_f32 v[12:13], v[20:21], v[6:7], v[12:13] op_sel_hi:[0,1,1]
	v_pk_fma_f32 v[4:5], v[22:23], v[4:5], v[8:9] op_sel_hi:[0,1,1] neg_lo:[0,0,1] neg_hi:[0,0,1]
	v_pk_fma_f32 v[6:7], v[22:23], v[6:7], v[10:11] op_sel_hi:[0,1,1] neg_lo:[0,0,1] neg_hi:[0,0,1]
	v_cndmask_b32_e64 v7, v13, v7, s[44:45]
	v_cndmask_b32_e64 v8, v12, v6, s[44:45]
	v_cndmask_b32_e64 v6, v15, v5, s[44:45]
	v_cndmask_b32_e64 v9, v14, v4, s[44:45]
	v_cvt_pk_bf16_f32 v4, v19, v18
	v_cvt_pk_bf16_f32 v5, v17, v16
	v_cvt_pk_bf16_f32 v6, v9, v6
	v_cvt_pk_bf16_f32 v7, v8, v7
